# LN1: per-column vectors staged in LDS, row loop re-loads them by ds_read_b128 and no longer waits on its stores (on top of MLA P.V interleave)
# baseline (speedup 1.0000x reference)
; __device__ __forceinline__ int otid() { int t = threadIdx.x; asm volatile("" : "+v"(t)); return t; }
; __device__ __forceinline__ void phase_ln(const float* z, float* xo, const float* __restrict__ g, const float* __restrict__ b, const float* __restrict__ sc, const float* __restrict__ sh, bf16_t* __restrict__ u) {
;     const int tid_o = otid(), lane = tid_o & 63, wave = tid_o >> 6;
;     const int stride = gridDim.x * 8;
;     for (int r = blockIdx.x * 8 + wave; r < S; r += 2 * stride) {
;         const bool hasB = r + stride < S; const int rr[2] = {r, hasB ? r + stride : r};
;         f32x4 v[2][8]; float s[2] = {0.f, 0.f};
; #pragma unroll
;         for (int k = 0; k < 2; ++k) { const float* zr = z + (size_t)rr[k] * DM;
; #pragma unroll
;             for (int j = 0; j < 8; ++j) v[k][j] = *(const f32x4*)(zr + j * 256 + 4 * lane); }
; #pragma unroll
;         for (int k = 0; k < 2; ++k)
; #pragma unroll
;             for (int j = 0; j < 8; ++j) s[k] += (v[k][j][0] + v[k][j][1]) + (v[k][j][2] + v[k][j][3]);
;         float mean[2], rstd[2];
; #pragma unroll
;         for (int k = 0; k < 2; ++k) { mean[k] = wave_sum(s[k]) * (1.0f / DM); float q = 0.f;
; #pragma unroll
;             for (int j = 0; j < 8; ++j) { const f32x4 d = v[k][j] - mean[k]; q += (d[0] * d[0] + d[1] * d[1]) + (d[2] * d[2] + d[3] * d[3]); }
;             rstd[k] = 1.0f / sqrtf(wave_sum(q) * (1.0f / DM) + 1e-5f); }
; #pragma unroll
;         for (int j = 0; j < 8; ++j) { const int col = j * 256 + 4 * lane;
;             const f32x4 gg = *(const f32x4*)(g + col), bb = *(const f32x4*)(b + col);
;             f32x4 s1 = {0.f, 0.f, 0.f, 0.f}, h1 = {0.f, 0.f, 0.f, 0.f};
;             if (u) { s1 = *(const f32x4*)(sc + col) + 1.0f; h1 = *(const f32x4*)(sh + col); }
.LBB0_1069:
	s_andn2_b64 vcc, exec, s[0:1]
	s_cbranch_vccnz .LBB0_1135
	v_readlane_b32 s0, v254, 43
	v_mov_b32_e32 v14, v216
	s_movk_i32 s17, 0x2000
	v_mov_b32_e32 v0, s0
	ds_read_b64 v[2:3], v0
	v_readlane_b32 s0, v254, 26
	s_waitcnt lgkmcnt(0)
	v_readfirstlane_b32 s2, v2
	v_mov_b32_e32 v0, s0
	v_readfirstlane_b32 s3, v3
	ds_read2_b64 v[2:5], v0 offset1:1
	v_readlane_b32 s0, v254, 9
	v_ashrrev_i32_e32 v0, 6, v14
	s_waitcnt lgkmcnt(0)
	v_readfirstlane_b32 s10, v2
	v_add_u32_e32 v80, s0, v0
	v_readfirstlane_b32 s11, v3
	v_readfirstlane_b32 s12, v4
	v_readfirstlane_b32 s13, v5
	v_readlane_b32 s14, v254, 46
	v_lshlrev_b32_e32 v253, 4, v14
	s_lshl_b32 s15, s14, 13
	s_add_u32 s0, s10, s15
	s_addc_u32 s1, s11, 0
	s_add_u32 s4, s12, s15
	s_addc_u32 s5, s13, 0
	s_mul_i32 s14, s14, 0xc000
	s_add_u32 s8, s2, s14
	s_addc_u32 s9, s3, 0
	s_add_u32 s8, s8, 0xb606000
	s_addc_u32 s9, s9, 0
	s_add_u32 s14, s8, 0x2000
	s_addc_u32 s15, s9, 0
	global_load_dwordx4 v[240:243], v253, s[0:1]
	global_load_dwordx4 v[244:247], v253, s[4:5]
	global_load_dwordx4 v[248:251], v253, s[14:15]
	global_load_dwordx4 v[236:239], v253, s[8:9]
	s_waitcnt vmcnt(0)
	ds_write_b128 v253, v[240:243]
	ds_write_b128 v253, v[244:247] offset:8192
	ds_write_b128 v253, v[248:251] offset:16384
	ds_write_b128 v253, v[236:239] offset:24576
	s_waitcnt lgkmcnt(0)
	s_barrier
	v_cmp_gt_i32_e32 vcc, s17, v80
	s_and_saveexec_b64 s[6:7], vcc
	v_readlane_b32 s16, v254, 10
	s_movk_i32 s18, 0x1000
	s_movk_i32 s19, 0x1fff
	v_readlane_b32 s20, v254, 48
	s_cbranch_execz .LBB0_1089
	v_readlane_b32 s14, v254, 46
	s_add_u32 s0, s2, 0xf828000
	s_mul_i32 s90, s14, 0x3000
	s_addc_u32 s1, s3, 0
	s_lshl_b64 s[4:5], s[90:91], 2
	s_add_u32 s8, s2, s4
	s_addc_u32 s9, s3, s5
	s_add_u32 s4, s8, 0xb606000
	s_addc_u32 s5, s9, 0
	s_add_u32 s8, s8, 0xb608000
	v_readlane_b32 s15, v254, 47
	s_addc_u32 s9, s9, 0
	s_lshl_b32 s90, s14, 11
	v_lshlrev_b32_e32 v0, 2, v14
	s_lshl_b64 s[14:15], s[90:91], 2
	v_and_b32_e32 v15, 0xfc, v0
	s_add_u32 s12, s12, s14
	v_lshlrev_b32_e32 v0, 2, v15
	v_mov_b32_e32 v252, v0
	s_addc_u32 s13, s13, s15
	v_lshl_add_u64 v[2:3], s[8:9], 0, v[0:1]
	s_add_u32 s10, s10, s14
	flat_load_dwordx4 v[16:19], v[2:3]
	s_addc_u32 s11, s11, s15
	v_lshl_add_u64 v[84:85], s[12:13], 0, v[0:1]
	v_lshl_add_u64 v[6:7], s[4:5], 0, v[0:1]
	v_lshl_add_u64 v[82:83], s[10:11], 0, v[0:1]
	flat_load_dwordx4 v[2:5], v[84:85]
	s_nop 0
	flat_load_dwordx4 v[6:9], v[6:7]
	s_nop 0
	flat_load_dwordx4 v[10:13], v[82:83]
	v_or_b32_e32 v35, 0x400, v15
	v_or_b32_e32 v36, 0x500, v15
	v_or_b32_e32 v37, 0x600, v15
	v_or_b32_e32 v38, 0x700, v15
	v_mov_b32_e32 v25, v1
	v_mov_b32_e32 v27, v1
	v_mov_b32_e32 v29, v1
	v_mov_b32_e32 v31, v1
	v_lshlrev_b32_e32 v24, 2, v35
	v_lshlrev_b32_e32 v26, 2, v36
	v_lshlrev_b32_e32 v28, 2, v37
	v_lshlrev_b32_e32 v30, 2, v38
	v_lshl_add_u64 v[110:111], s[12:13], 0, v[24:25]
	v_lshl_add_u64 v[112:113], s[12:13], 0, v[26:27]
	v_lshl_add_u64 v[114:115], s[12:13], 0, v[28:29]
	v_lshl_add_u64 v[116:117], s[12:13], 0, v[30:31]
	s_add_u32 s12, s2, 0xb828000
	s_addc_u32 s13, s3, 0
	v_or_b32_e32 v32, 0x100, v15
	v_lshl_add_u64 v[126:127], s[12:13], 0, v[0:1]
	v_lshlrev_b32_e32 v0, 1, v15
	v_lshl_add_u64 v[140:141], s[0:1], 0, v[0:1]
	v_lshlrev_b32_e32 v0, 2, v32
	v_or_b32_e32 v33, 0x200, v15
	v_lshl_add_u64 v[142:143], s[4:5], 0, v[0:1]
	v_lshl_add_u64 v[144:145], s[8:9], 0, v[0:1]
	v_lshl_add_u64 v[146:147], s[12:13], 0, v[0:1]
	v_lshlrev_b32_e32 v0, 1, v32
	v_or_b32_e32 v34, 0x300, v15
	v_lshl_add_u64 v[148:149], s[0:1], 0, v[0:1]
	v_lshlrev_b32_e32 v0, 1, v33
	v_lshl_add_u64 v[150:151], s[0:1], 0, v[0:1]
	v_lshlrev_b32_e32 v0, 1, v34
	v_lshl_add_u64 v[152:153], s[0:1], 0, v[0:1]
	v_lshlrev_b32_e32 v0, 1, v35
	v_lshl_add_u64 v[158:159], s[0:1], 0, v[0:1]
	v_lshlrev_b32_e32 v0, 1, v36
	v_lshl_add_u64 v[160:161], s[0:1], 0, v[0:1]
	v_lshlrev_b32_e32 v0, 1, v37
	v_lshl_add_u64 v[162:163], s[0:1], 0, v[0:1]
	v_lshlrev_b32_e32 v0, 1, v38
	v_ashrrev_i32_e32 v81, 31, v80
	v_mov_b32_e32 v21, v1
	v_mov_b32_e32 v23, v1
	v_lshlrev_b32_e32 v20, 2, v33
	v_lshlrev_b32_e32 v22, 2, v34
	v_lshl_add_u64 v[164:165], s[0:1], 0, v[0:1]
	v_lshlrev_b64 v[166:167], 12, v[80:81]
	v_and_b32_e32 v0, 63, v14
	v_lshlrev_b64 v[168:169], 13, v[80:81]
	v_lshl_add_u64 v[86:87], s[4:5], 0, v[20:21]
	v_lshl_add_u64 v[88:89], s[4:5], 0, v[22:23]
	v_lshl_add_u64 v[90:91], s[4:5], 0, v[24:25]
	v_lshl_add_u64 v[92:93], s[4:5], 0, v[26:27]
	v_lshl_add_u64 v[94:95], s[4:5], 0, v[28:29]
	v_lshl_add_u64 v[96:97], s[4:5], 0, v[30:31]
	v_lshl_add_u64 v[98:99], s[8:9], 0, v[20:21]
	v_lshl_add_u64 v[100:101], s[8:9], 0, v[22:23]
	v_lshl_add_u64 v[102:103], s[8:9], 0, v[24:25]
	v_lshl_add_u64 v[104:105], s[8:9], 0, v[26:27]
	v_lshl_add_u64 v[106:107], s[8:9], 0, v[28:29]
	v_lshl_add_u64 v[108:109], s[8:9], 0, v[30:31]
	v_lshl_add_u64 v[118:119], s[10:11], 0, v[24:25]
	v_lshl_add_u64 v[120:121], s[10:11], 0, v[26:27]
	v_lshl_add_u64 v[122:123], s[10:11], 0, v[28:29]
	v_lshl_add_u64 v[124:125], s[10:11], 0, v[30:31]
	v_lshl_add_u64 v[128:129], s[12:13], 0, v[24:25]
	v_lshl_add_u64 v[130:131], s[12:13], 0, v[26:27]
	v_lshl_add_u64 v[132:133], s[12:13], 0, v[28:29]
	v_lshl_add_u64 v[134:135], s[12:13], 0, v[30:31]
	v_lshl_add_u64 v[136:137], s[12:13], 0, v[20:21]
	v_lshl_add_u64 v[138:139], s[12:13], 0, v[22:23]
	v_lshl_or_b32 v166, v0, 3, v166
	s_waitcnt vmcnt(0) lgkmcnt(0)
	v_pk_add_f32 v[154:155], v[18:19], 1.0 op_sel_hi:[1,0]
	v_pk_add_f32 v[156:157], v[16:17], 1.0 op_sel_hi:[1,0]
	v_lshl_or_b32 v168, v0, 4, v168
	s_mov_b64 s[8:9], 0
	s_branch .LBB0_1073

; __device__ __forceinline__ unsigned cvt_pk_bf16(float lo, float hi) { unsigned r; asm volatile("v_cvt_pk_bf16_f32 %0, %1, %2" : "=v"(r) : "v"(lo), "v"(hi)); return r; }
; __device__ __forceinline__ void phase_ln(const float* z, float* xo, const float* __restrict__ g, const float* __restrict__ b, const float* __restrict__ sc, const float* __restrict__ sh, bf16_t* __restrict__ u) {
;     ...
;         for (int j = 0; j < 8; ++j) { const int col = j * 256 + 4 * lane;
;             const f32x4 gg = *(const f32x4*)(g + col), bb = *(const f32x4*)(b + col);
;             f32x4 s1 = {0.f, 0.f, 0.f, 0.f}, h1 = {0.f, 0.f, 0.f, 0.f};
;             if (u) { s1 = *(const f32x4*)(sc + col) + 1.0f; h1 = *(const f32x4*)(sh + col); }
; #pragma unroll
;             for (int k = 0; k < 2; ++k) { if (k == 1 && !hasB) continue;
;                 const f32x4 o = (v[k][j] - mean[k]) * rstd[k] * gg + bb;
;                 *(f32x4*)(xo + (size_t)rr[k] * DM + col) = o;
;                 if (u) { const f32x4 m = o * s1 + h1; u32x2 w; w.x = cvt_pk_bf16(m[0], m[1]); w.y = cvt_pk_bf16(m[2], m[3]); *(u32x2*)(u + (size_t)rr[k] * DM + col) = w; } } }
.LBB0_1075:
	s_or_b64 exec, exec, s[0:1]
	ds_read_b128 v[68:71], v252 offset:1024
	ds_read_b128 v[72:75], v252 offset:9216
	ds_read_b128 v[76:79], v252 offset:17408
	v_mov_b32_e32 v177, v176
	v_mov_b32_e32 v24, v176
	v_mov_b32_e32 v25, v176
	s_mov_b64 s[0:1], 0xb828400
	v_pk_mul_f32 v[56:57], v[202:203], v[24:25]
	v_pk_mul_f32 v[64:65], v[66:67], v[176:177]
	v_lshl_add_u64 v[48:49], v[172:173], 0, s[0:1]
	s_waitcnt lgkmcnt(0)
	v_pk_fma_f32 v[66:67], v[56:57], v[70:71], v[74:75]
	v_pk_add_f32 v[32:33], v[78:79], 1.0 op_sel_hi:[1,0]
	v_pk_add_f32 v[40:41], v[76:77], 1.0 op_sel_hi:[1,0]
	ds_read_b128 v[76:79], v252 offset:25600
	v_pk_fma_f32 v[64:65], v[64:65], v[68:69], v[72:73]
	flat_store_dwordx4 v[48:49], v[64:67]
	s_waitcnt lgkmcnt(0)
	v_pk_fma_f32 v[48:49], v[66:67], v[32:33], v[78:79]
	v_pk_fma_f32 v[56:57], v[64:65], v[40:41], v[76:77]
	s_nop 0
	v_cvt_pk_bf16_f32 v56, v56, v57
	v_cvt_pk_bf16_f32 v57, v48, v49
	v_add_co_u32_e32 v48, vcc, 0xf828000, v184
	s_nop 1
	v_addc_co_u32_e32 v49, vcc, 0, v185, vcc
	flat_store_dwordx2 v[48:49], v[56:57] offset:512
	s_and_saveexec_b64 s[0:1], s[4:5]
	s_cbranch_execz .LBB0_1077
	v_pk_mul_f32 v[48:49], v[60:61], v[0:1] op_sel_hi:[1,0]
	v_pk_mul_f32 v[56:57], v[62:63], v[0:1] op_sel_hi:[1,0]
	v_pk_fma_f32 v[62:63], v[48:49], v[70:71], v[74:75]
	v_pk_fma_f32 v[60:61], v[56:57], v[68:69], v[72:73]
	v_lshl_add_u64 v[48:49], v[146:147], 0, v[170:171]
	v_pk_fma_f32 v[32:33], v[62:63], v[32:33], v[78:79]
	v_pk_fma_f32 v[40:41], v[60:61], v[40:41], v[76:77]
	flat_store_dwordx4 v[48:49], v[60:63]
	v_cvt_pk_bf16_f32 v40, v40, v41
	v_cvt_pk_bf16_f32 v41, v32, v33
	v_lshl_add_u64 v[32:33], v[148:149], 0, v[182:183]
	flat_store_dwordx2 v[32:33], v[40:41]
.LBB0_1077:
	s_or_b64 exec, exec, s[0:1]
	ds_read_b128 v[72:75], v252 offset:18432
	ds_read_b128 v[64:67], v252 offset:2048
	ds_read_b128 v[68:71], v252 offset:10240
	ds_read_b128 v[60:63], v252 offset:26624
	v_pk_mul_f32 v[48:49], v[58:59], v[176:177]
	s_mov_b64 s[0:1], 0xb828800
	v_pk_mul_f32 v[40:41], v[200:201], v[24:25]
	v_add_co_u32_e32 v76, vcc, 0xf828000, v184
	v_lshl_add_u64 v[78:79], v[172:173], 0, s[0:1]
	s_nop 0
	v_addc_co_u32_e32 v77, vcc, 0, v185, vcc
	s_waitcnt lgkmcnt(0)
	v_pk_add_f32 v[32:33], v[72:73], 1.0 op_sel_hi:[1,0]
	v_pk_add_f32 v[24:25], v[74:75], 1.0 op_sel_hi:[1,0]
	v_pk_fma_f32 v[56:57], v[48:49], v[64:65], v[68:69]
	v_pk_fma_f32 v[58:59], v[40:41], v[66:67], v[70:71]
	v_pk_fma_f32 v[48:49], v[56:57], v[32:33], v[60:61]
	flat_store_dwordx4 v[78:79], v[56:59]
	v_pk_fma_f32 v[40:41], v[58:59], v[24:25], v[62:63]
	v_cvt_pk_bf16_f32 v48, v48, v49
	s_nop 0
	v_cvt_pk_bf16_f32 v49, v40, v41
	flat_store_dwordx2 v[76:77], v[48:49] offset:1024
	s_and_saveexec_b64 s[0:1], s[4:5]
	s_cbranch_execz .LBB0_1079
	v_pk_mul_f32 v[40:41], v[52:53], v[0:1] op_sel_hi:[1,0]
	v_pk_mul_f32 v[48:49], v[54:55], v[0:1] op_sel_hi:[1,0]
	v_pk_fma_f32 v[54:55], v[40:41], v[66:67], v[70:71]
	v_pk_fma_f32 v[52:53], v[48:49], v[64:65], v[68:69]
	v_lshl_add_u64 v[40:41], v[136:137], 0, v[170:171]
	v_pk_fma_f32 v[24:25], v[54:55], v[24:25], v[62:63]
	v_pk_fma_f32 v[32:33], v[52:53], v[32:33], v[60:61]
	flat_store_dwordx4 v[40:41], v[52:55]
	v_cvt_pk_bf16_f32 v32, v32, v33
	v_cvt_pk_bf16_f32 v33, v24, v25
	v_lshl_add_u64 v[24:25], v[150:151], 0, v[182:183]
	flat_store_dwordx2 v[24:25], v[32:33]
.LBB0_1079:
	s_or_b64 exec, exec, s[0:1]
	ds_read_b128 v[52:55], v252 offset:3072
	ds_read_b128 v[56:59], v252 offset:11264
	ds_read_b128 v[60:63], v252 offset:19456
	v_mov_b32_e32 v24, v176
	v_mov_b32_e32 v25, v176
	s_mov_b64 s[0:1], 0xb828c00
	v_pk_mul_f32 v[48:49], v[196:197], v[24:25]
	v_pk_mul_f32 v[66:67], v[50:51], v[176:177]
	v_lshl_add_u64 v[64:65], v[172:173], 0, s[0:1]
	s_waitcnt lgkmcnt(0)
	v_pk_fma_f32 v[50:51], v[48:49], v[54:55], v[58:59]
	v_pk_add_f32 v[32:33], v[62:63], 1.0 op_sel_hi:[1,0]
	v_pk_add_f32 v[40:41], v[60:61], 1.0 op_sel_hi:[1,0]
	ds_read_b128 v[60:63], v252 offset:27648
	v_pk_fma_f32 v[48:49], v[66:67], v[52:53], v[56:57]
	flat_store_dwordx4 v[64:65], v[48:51]
	s_waitcnt lgkmcnt(0)
	s_nop 0
	v_pk_fma_f32 v[50:51], v[50:51], v[32:33], v[62:63]
	v_pk_fma_f32 v[48:49], v[48:49], v[40:41], v[60:61]
	s_nop 0
	v_cvt_pk_bf16_f32 v48, v48, v49
	v_cvt_pk_bf16_f32 v49, v50, v51
	v_add_co_u32_e32 v50, vcc, 0xf828000, v184
	s_nop 1
	v_addc_co_u32_e32 v51, vcc, 0, v185, vcc
	flat_store_dwordx2 v[50:51], v[48:49] offset:1536
	s_and_saveexec_b64 s[0:1], s[4:5]
	s_cbranch_execz .LBB0_1081
	v_pk_mul_f32 v[44:45], v[44:45], v[0:1] op_sel_hi:[1,0]
	v_pk_mul_f32 v[48:49], v[46:47], v[0:1] op_sel_hi:[1,0]
	v_pk_fma_f32 v[46:47], v[44:45], v[54:55], v[58:59]
	v_pk_fma_f32 v[44:45], v[48:49], v[52:53], v[56:57]
	v_lshl_add_u64 v[48:49], v[138:139], 0, v[170:171]
	v_pk_fma_f32 v[32:33], v[46:47], v[32:33], v[62:63]
	v_pk_fma_f32 v[40:41], v[44:45], v[40:41], v[60:61]
	flat_store_dwordx4 v[48:49], v[44:47]
	v_cvt_pk_bf16_f32 v40, v40, v41
	v_cvt_pk_bf16_f32 v41, v32, v33
	v_lshl_add_u64 v[32:33], v[152:153], 0, v[182:183]
	flat_store_dwordx2 v[32:33], v[40:41]
; __device__ __forceinline__ unsigned cvt_pk_bf16(float lo, float hi) { unsigned r; asm volatile("v_cvt_pk_bf16_f32 %0, %1, %2" : "=v"(r) : "v"(lo), "v"(hi)); return r; }
; __device__ __forceinline__ void phase_ln(const float* z, float* xo, const float* __restrict__ g, const float* __restrict__ b, const float* __restrict__ sc, const float* __restrict__ sh, bf16_t* __restrict__ u) {
;     ...
;         for (int j = 0; j < 8; ++j) { const int col = j * 256 + 4 * lane;
;             const f32x4 gg = *(const f32x4*)(g + col), bb = *(const f32x4*)(b + col);
;             f32x4 s1 = {0.f, 0.f, 0.f, 0.f}, h1 = {0.f, 0.f, 0.f, 0.f};
;             if (u) { s1 = *(const f32x4*)(sc + col) + 1.0f; h1 = *(const f32x4*)(sh + col); }
; #pragma unroll
;             for (int k = 0; k < 2; ++k) { if (k == 1 && !hasB) continue;
;                 const f32x4 o = (v[k][j] - mean[k]) * rstd[k] * gg + bb;
;                 *(f32x4*)(xo + (size_t)rr[k] * DM + col) = o;
;                 if (u) { const f32x4 m = o * s1 + h1; u32x2 w; w.x = cvt_pk_bf16(m[0], m[1]); w.y = cvt_pk_bf16(m[2], m[3]); *(u32x2*)(u + (size_t)rr[k] * DM + col) = w; } } }
.LBB0_1081:
	s_or_b64 exec, exec, s[0:1]
	ds_read_b128 v[56:59], v252 offset:20480
	ds_read_b128 v[48:51], v252 offset:4096
	ds_read_b128 v[52:55], v252 offset:12288
	ds_read_b128 v[44:47], v252 offset:28672
	s_mov_b64 s[0:1], 0xb829000
	v_pk_mul_f32 v[40:41], v[194:195], v[24:25]
	v_pk_mul_f32 v[60:61], v[42:43], v[176:177]
	v_add_co_u32_e32 v62, vcc, 0xf828000, v184
	v_lshl_add_u64 v[64:65], v[172:173], 0, s[0:1]
	s_nop 0
	v_addc_co_u32_e32 v63, vcc, 0, v185, vcc
	s_waitcnt lgkmcnt(0)
	v_pk_add_f32 v[32:33], v[56:57], 1.0 op_sel_hi:[1,0]
	v_pk_add_f32 v[24:25], v[58:59], 1.0 op_sel_hi:[1,0]
	v_pk_fma_f32 v[42:43], v[40:41], v[50:51], v[54:55]
	v_pk_fma_f32 v[40:41], v[60:61], v[48:49], v[52:53]
	flat_store_dwordx4 v[64:65], v[40:43]
	s_nop 1
	v_pk_fma_f32 v[40:41], v[40:41], v[32:33], v[44:45]
	v_pk_fma_f32 v[42:43], v[42:43], v[24:25], v[46:47]
	v_cvt_pk_bf16_f32 v40, v40, v41
	s_nop 0
	v_cvt_pk_bf16_f32 v41, v42, v43
	flat_store_dwordx2 v[62:63], v[40:41] offset:2048
	s_and_saveexec_b64 s[0:1], s[4:5]
	s_cbranch_execz .LBB0_1083
	v_pk_mul_f32 v[36:37], v[36:37], v[0:1] op_sel_hi:[1,0]
	v_pk_mul_f32 v[40:41], v[38:39], v[0:1] op_sel_hi:[1,0]
	v_pk_fma_f32 v[38:39], v[36:37], v[50:51], v[54:55]
	v_pk_fma_f32 v[36:37], v[40:41], v[48:49], v[52:53]
	v_lshl_add_u64 v[40:41], v[128:129], 0, v[170:171]
	v_pk_fma_f32 v[24:25], v[38:39], v[24:25], v[46:47]
	v_pk_fma_f32 v[32:33], v[36:37], v[32:33], v[44:45]
	flat_store_dwordx4 v[40:41], v[36:39]
	v_cvt_pk_bf16_f32 v32, v32, v33
	v_cvt_pk_bf16_f32 v33, v24, v25
	v_lshl_add_u64 v[24:25], v[158:159], 0, v[182:183]
	flat_store_dwordx2 v[24:25], v[32:33]
.LBB0_1083:
	s_or_b64 exec, exec, s[0:1]
	ds_read_b128 v[36:39], v252 offset:5120
	ds_read_b128 v[40:43], v252 offset:13312
	ds_read_b128 v[44:47], v252 offset:21504
	v_mov_b32_e32 v24, v176
	v_mov_b32_e32 v25, v176
	s_mov_b64 s[0:1], 0xb829400
	v_pk_mul_f32 v[50:51], v[180:181], v[24:25]
	v_pk_mul_f32 v[34:35], v[34:35], v[176:177]
	v_lshl_add_u64 v[54:55], v[172:173], 0, s[0:1]
	s_waitcnt lgkmcnt(0)
	v_pk_fma_f32 v[52:53], v[50:51], v[38:39], v[42:43]
	v_pk_add_f32 v[32:33], v[46:47], 1.0 op_sel_hi:[1,0]
	v_pk_add_f32 v[48:49], v[44:45], 1.0 op_sel_hi:[1,0]
	ds_read_b128 v[44:47], v252 offset:29696
	v_pk_fma_f32 v[50:51], v[34:35], v[36:37], v[40:41]
	flat_store_dwordx4 v[54:55], v[50:53]
	s_waitcnt lgkmcnt(0)
	v_pk_fma_f32 v[34:35], v[52:53], v[32:33], v[46:47]
	v_pk_fma_f32 v[50:51], v[50:51], v[48:49], v[44:45]
	s_nop 0
	v_cvt_pk_bf16_f32 v50, v50, v51
	v_cvt_pk_bf16_f32 v51, v34, v35
	v_add_co_u32_e32 v34, vcc, 0xf828000, v184
	s_nop 1
	v_addc_co_u32_e32 v35, vcc, 0, v185, vcc
	flat_store_dwordx2 v[34:35], v[50:51] offset:2560
	s_and_saveexec_b64 s[0:1], s[4:5]
	s_cbranch_execz .LBB0_1085
	v_pk_mul_f32 v[28:29], v[28:29], v[0:1] op_sel_hi:[1,0]
	v_pk_mul_f32 v[34:35], v[30:31], v[0:1] op_sel_hi:[1,0]
	v_pk_fma_f32 v[30:31], v[28:29], v[38:39], v[42:43]
	v_pk_fma_f32 v[28:29], v[34:35], v[36:37], v[40:41]
	v_lshl_add_u64 v[34:35], v[130:131], 0, v[170:171]
	flat_store_dwordx4 v[34:35], v[28:31]
	s_nop 1
	v_pk_fma_f32 v[30:31], v[30:31], v[32:33], v[46:47]
	v_pk_fma_f32 v[28:29], v[28:29], v[48:49], v[44:45]
	s_nop 0
	v_cvt_pk_bf16_f32 v28, v28, v29
	v_cvt_pk_bf16_f32 v29, v30, v31
	v_lshl_add_u64 v[30:31], v[160:161], 0, v[182:183]
	flat_store_dwordx2 v[30:31], v[28:29]
.LBB0_1085:
	s_or_b64 exec, exec, s[0:1]
	ds_read_b128 v[40:43], v252 offset:22528
	ds_read_b128 v[32:35], v252 offset:6144
	ds_read_b128 v[36:39], v252 offset:14336
	ds_read_b128 v[28:31], v252 offset:30720
	s_mov_b64 s[0:1], 0xb829800
	v_pk_mul_f32 v[44:45], v[178:179], v[24:25]
	v_pk_mul_f32 v[46:47], v[26:27], v[176:177]
	v_add_co_u32_e32 v48, vcc, 0xf828000, v184
	v_lshl_add_u64 v[50:51], v[172:173], 0, s[0:1]
	s_nop 0
	v_addc_co_u32_e32 v49, vcc, 0, v185, vcc
	s_waitcnt lgkmcnt(0)
	v_pk_add_f32 v[24:25], v[42:43], 1.0 op_sel_hi:[1,0]
	v_pk_add_f32 v[26:27], v[40:41], 1.0 op_sel_hi:[1,0]
	v_pk_fma_f32 v[42:43], v[44:45], v[34:35], v[38:39]
	v_pk_fma_f32 v[40:41], v[46:47], v[32:33], v[36:37]
	flat_store_dwordx4 v[50:51], v[40:43]
	s_nop 1
	v_pk_fma_f32 v[40:41], v[40:41], v[26:27], v[28:29]
	v_pk_fma_f32 v[42:43], v[42:43], v[24:25], v[30:31]
	v_cvt_pk_bf16_f32 v40, v40, v41
	s_nop 0
	v_cvt_pk_bf16_f32 v41, v42, v43
	flat_store_dwordx2 v[48:49], v[40:41] offset:3072
	s_and_saveexec_b64 s[0:1], s[4:5]
	s_cbranch_execz .LBB0_1087
	v_pk_mul_f32 v[20:21], v[20:21], v[0:1] op_sel_hi:[1,0]
	v_pk_mul_f32 v[40:41], v[22:23], v[0:1] op_sel_hi:[1,0]
	v_pk_fma_f32 v[22:23], v[20:21], v[34:35], v[38:39]
	v_pk_fma_f32 v[20:21], v[40:41], v[32:33], v[36:37]
	v_lshl_add_u64 v[32:33], v[132:133], 0, v[170:171]
	flat_store_dwordx4 v[32:33], v[20:23]
	s_nop 1
	v_pk_fma_f32 v[22:23], v[22:23], v[24:25], v[30:31]
	v_pk_fma_f32 v[20:21], v[20:21], v[26:27], v[28:29]
	s_nop 0
	v_cvt_pk_bf16_f32 v20, v20, v21
	v_cvt_pk_bf16_f32 v21, v22, v23
	v_lshl_add_u64 v[22:23], v[162:163], 0, v[182:183]
	flat_store_dwordx2 v[22:23], v[20:21]
.LBB0_1087:
	s_or_b64 exec, exec, s[0:1]
	ds_read_b128 v[32:35], v252 offset:23552
	ds_read_b128 v[24:27], v252 offset:7168
	ds_read_b128 v[28:31], v252 offset:15360
	ds_read_b128 v[20:23], v252 offset:31744
	v_mov_b32_e32 v36, v176
	v_mov_b32_e32 v37, v176
	s_mov_b64 s[0:1], 0xb829c00
	v_pk_mul_f32 v[40:41], v[18:19], v[176:177]
	v_pk_mul_f32 v[36:37], v[174:175], v[36:37]
	v_lshl_add_u64 v[38:39], v[172:173], 0, s[0:1]
	v_add_co_u32_e32 v42, vcc, 0xf828000, v184
	s_waitcnt lgkmcnt(0)
	v_pk_add_f32 v[18:19], v[34:35], 1.0 op_sel_hi:[1,0]
	v_pk_add_f32 v[32:33], v[32:33], 1.0 op_sel_hi:[1,0]
	v_pk_fma_f32 v[36:37], v[36:37], v[26:27], v[30:31]
	v_pk_fma_f32 v[34:35], v[40:41], v[24:25], v[28:29]
	flat_store_dwordx4 v[38:39], v[34:37]
	v_addc_co_u32_e32 v43, vcc, 0, v185, vcc
	s_nop 0
	v_pk_fma_f32 v[34:35], v[34:35], v[32:33], v[20:21]
	v_pk_fma_f32 v[36:37], v[36:37], v[18:19], v[22:23]
	v_cvt_pk_bf16_f32 v34, v34, v35
	s_nop 0
	v_cvt_pk_bf16_f32 v35, v36, v37
	flat_store_dwordx2 v[42:43], v[34:35] offset:3584
	s_and_saveexec_b64 s[0:1], s[4:5]
	s_cbranch_execz .LBB0_1072
	v_pk_mul_f32 v[16:17], v[16:17], v[0:1] op_sel_hi:[1,0]
	v_pk_mul_f32 v[14:15], v[14:15], v[0:1] op_sel_hi:[1,0]
	v_pk_fma_f32 v[16:17], v[16:17], v[26:27], v[30:31]
	v_pk_fma_f32 v[14:15], v[14:15], v[24:25], v[28:29]
	v_lshl_add_u64 v[24:25], v[134:135], 0, v[170:171]
	flat_store_dwordx4 v[24:25], v[14:17]
	s_nop 1
	v_pk_fma_f32 v[16:17], v[16:17], v[18:19], v[22:23]
	v_pk_fma_f32 v[14:15], v[14:15], v[32:33], v[20:21]
	s_nop 0
	v_cvt_pk_bf16_f32 v14, v14, v15
	v_cvt_pk_bf16_f32 v15, v16, v17
	v_lshl_add_u64 v[16:17], v[164:165], 0, v[182:183]
	flat_store_dwordx2 v[16:17], v[14:15]
	s_branch .LBB0_1072
